# block-means loop with 16 loads in flight + batched LN mean/rstd LDS reads (on peeled-loop version)
# speedup vs baseline: 1.0054x; 1.0054x over previous
.LBB0_251:
	v_lshl_add_u64 v[16:17], v[6:7], 0, s[8:9]
	v_add_co_u32_e32 v18, vcc, 0xf600000, v16
	s_nop 1
	v_addc_co_u32_e32 v19, vcc, 0, v17, vcc
	v_mov_b32_e32 v20, 0xc000
	v_mov_b32_e32 v21, 0
	global_load_dwordx4 v[46:49], v[18:19], off offset:2048
	v_lshl_add_u64 v[18:19], v[18:19], 0, v[20:21]
	global_load_dwordx4 v[50:53], v[18:19], off offset:2048
	v_lshl_add_u64 v[18:19], v[18:19], 0, v[20:21]
	global_load_dwordx4 v[54:57], v[18:19], off offset:2048
	v_lshl_add_u64 v[18:19], v[18:19], 0, v[20:21]
	global_load_dwordx4 v[58:61], v[18:19], off offset:2048
	v_lshl_add_u64 v[18:19], v[18:19], 0, v[20:21]
	global_load_dwordx4 v[62:65], v[18:19], off offset:2048
	v_lshl_add_u64 v[18:19], v[18:19], 0, v[20:21]
	global_load_dwordx4 v[66:69], v[18:19], off offset:2048
	v_lshl_add_u64 v[18:19], v[18:19], 0, v[20:21]
	global_load_dwordx4 v[70:73], v[18:19], off offset:2048
	v_lshl_add_u64 v[18:19], v[18:19], 0, v[20:21]
	global_load_dwordx4 v[74:77], v[18:19], off offset:2048
	v_lshl_add_u64 v[18:19], v[18:19], 0, v[20:21]
	global_load_dwordx4 v[78:81], v[18:19], off offset:2048
	v_lshl_add_u64 v[18:19], v[18:19], 0, v[20:21]
	global_load_dwordx4 v[82:85], v[18:19], off offset:2048
	v_lshl_add_u64 v[18:19], v[18:19], 0, v[20:21]
	global_load_dwordx4 v[86:89], v[18:19], off offset:2048
	v_lshl_add_u64 v[18:19], v[18:19], 0, v[20:21]
	global_load_dwordx4 v[90:93], v[18:19], off offset:2048
	v_lshl_add_u64 v[18:19], v[18:19], 0, v[20:21]
	global_load_dwordx4 v[94:97], v[18:19], off offset:2048
	v_lshl_add_u64 v[18:19], v[18:19], 0, v[20:21]
	global_load_dwordx4 v[98:101], v[18:19], off offset:2048
	v_lshl_add_u64 v[18:19], v[18:19], 0, v[20:21]
	global_load_dwordx4 v[102:105], v[18:19], off offset:2048
	v_lshl_add_u64 v[18:19], v[18:19], 0, v[20:21]
	global_load_dwordx4 v[106:109], v[18:19], off offset:2048
	s_add_u32 s8, s8, 0xc0000
	s_addc_u32 s9, s9, 0
	s_waitcnt vmcnt(15)
	v_lshlrev_b32_e32 v24, 16, v46
	v_and_b32_e32 v25, 0xffff0000, v46
	v_pk_add_f32 v[14:15], v[14:15], v[24:25]
	v_lshlrev_b32_e32 v24, 16, v47
	v_and_b32_e32 v25, 0xffff0000, v47
	v_pk_add_f32 v[12:13], v[12:13], v[24:25]
	v_lshlrev_b32_e32 v24, 16, v48
	v_and_b32_e32 v25, 0xffff0000, v48
	v_pk_add_f32 v[10:11], v[10:11], v[24:25]
	v_lshlrev_b32_e32 v24, 16, v49
	v_and_b32_e32 v25, 0xffff0000, v49
	v_pk_add_f32 v[8:9], v[8:9], v[24:25]
	s_waitcnt vmcnt(14)
	v_lshlrev_b32_e32 v24, 16, v50
	v_and_b32_e32 v25, 0xffff0000, v50
	v_pk_add_f32 v[14:15], v[14:15], v[24:25]
	v_lshlrev_b32_e32 v24, 16, v51
	v_and_b32_e32 v25, 0xffff0000, v51
	v_pk_add_f32 v[12:13], v[12:13], v[24:25]
	v_lshlrev_b32_e32 v24, 16, v52
	v_and_b32_e32 v25, 0xffff0000, v52
	v_pk_add_f32 v[10:11], v[10:11], v[24:25]
	v_lshlrev_b32_e32 v24, 16, v53
	v_and_b32_e32 v25, 0xffff0000, v53
	v_pk_add_f32 v[8:9], v[8:9], v[24:25]
	s_waitcnt vmcnt(13)
	v_lshlrev_b32_e32 v24, 16, v54
	v_and_b32_e32 v25, 0xffff0000, v54
	v_pk_add_f32 v[14:15], v[14:15], v[24:25]
	v_lshlrev_b32_e32 v24, 16, v55
	v_and_b32_e32 v25, 0xffff0000, v55
	v_pk_add_f32 v[12:13], v[12:13], v[24:25]
	v_lshlrev_b32_e32 v24, 16, v56
	v_and_b32_e32 v25, 0xffff0000, v56
	v_pk_add_f32 v[10:11], v[10:11], v[24:25]
	v_lshlrev_b32_e32 v24, 16, v57
	v_and_b32_e32 v25, 0xffff0000, v57
	v_pk_add_f32 v[8:9], v[8:9], v[24:25]
	s_waitcnt vmcnt(12)
	v_lshlrev_b32_e32 v24, 16, v58
	v_and_b32_e32 v25, 0xffff0000, v58
	v_pk_add_f32 v[14:15], v[14:15], v[24:25]
	v_lshlrev_b32_e32 v24, 16, v59
	v_and_b32_e32 v25, 0xffff0000, v59
	v_pk_add_f32 v[12:13], v[12:13], v[24:25]
	v_lshlrev_b32_e32 v24, 16, v60
	v_and_b32_e32 v25, 0xffff0000, v60
	v_pk_add_f32 v[10:11], v[10:11], v[24:25]
	v_lshlrev_b32_e32 v24, 16, v61
	v_and_b32_e32 v25, 0xffff0000, v61
	v_pk_add_f32 v[8:9], v[8:9], v[24:25]
	s_waitcnt vmcnt(11)
	v_lshlrev_b32_e32 v24, 16, v62
	v_and_b32_e32 v25, 0xffff0000, v62
	v_pk_add_f32 v[14:15], v[14:15], v[24:25]
	v_lshlrev_b32_e32 v24, 16, v63
	v_and_b32_e32 v25, 0xffff0000, v63
	v_pk_add_f32 v[12:13], v[12:13], v[24:25]
	v_lshlrev_b32_e32 v24, 16, v64
	v_and_b32_e32 v25, 0xffff0000, v64
	v_pk_add_f32 v[10:11], v[10:11], v[24:25]
	v_lshlrev_b32_e32 v24, 16, v65
	v_and_b32_e32 v25, 0xffff0000, v65
	v_pk_add_f32 v[8:9], v[8:9], v[24:25]
	s_waitcnt vmcnt(10)
	v_lshlrev_b32_e32 v24, 16, v66
	v_and_b32_e32 v25, 0xffff0000, v66
	v_pk_add_f32 v[14:15], v[14:15], v[24:25]
	v_lshlrev_b32_e32 v24, 16, v67
	v_and_b32_e32 v25, 0xffff0000, v67
	v_pk_add_f32 v[12:13], v[12:13], v[24:25]
	v_lshlrev_b32_e32 v24, 16, v68
	v_and_b32_e32 v25, 0xffff0000, v68
	v_pk_add_f32 v[10:11], v[10:11], v[24:25]
	v_lshlrev_b32_e32 v24, 16, v69
	v_and_b32_e32 v25, 0xffff0000, v69
	v_pk_add_f32 v[8:9], v[8:9], v[24:25]
	s_waitcnt vmcnt(9)
	v_lshlrev_b32_e32 v24, 16, v70
	v_and_b32_e32 v25, 0xffff0000, v70
	v_pk_add_f32 v[14:15], v[14:15], v[24:25]
	v_lshlrev_b32_e32 v24, 16, v71
	v_and_b32_e32 v25, 0xffff0000, v71
	v_pk_add_f32 v[12:13], v[12:13], v[24:25]
	v_lshlrev_b32_e32 v24, 16, v72
	v_and_b32_e32 v25, 0xffff0000, v72
	v_pk_add_f32 v[10:11], v[10:11], v[24:25]
	v_lshlrev_b32_e32 v24, 16, v73
	v_and_b32_e32 v25, 0xffff0000, v73
	v_pk_add_f32 v[8:9], v[8:9], v[24:25]
	s_waitcnt vmcnt(8)
	v_lshlrev_b32_e32 v24, 16, v74
	v_and_b32_e32 v25, 0xffff0000, v74
	v_pk_add_f32 v[14:15], v[14:15], v[24:25]
	v_lshlrev_b32_e32 v24, 16, v75
	v_and_b32_e32 v25, 0xffff0000, v75
	v_pk_add_f32 v[12:13], v[12:13], v[24:25]
	v_lshlrev_b32_e32 v24, 16, v76
	v_and_b32_e32 v25, 0xffff0000, v76
	v_pk_add_f32 v[10:11], v[10:11], v[24:25]
	v_lshlrev_b32_e32 v24, 16, v77
	v_and_b32_e32 v25, 0xffff0000, v77
	v_pk_add_f32 v[8:9], v[8:9], v[24:25]
	s_waitcnt vmcnt(7)
	v_lshlrev_b32_e32 v24, 16, v78
	v_and_b32_e32 v25, 0xffff0000, v78
	v_pk_add_f32 v[14:15], v[14:15], v[24:25]
	v_lshlrev_b32_e32 v24, 16, v79
	v_and_b32_e32 v25, 0xffff0000, v79
	v_pk_add_f32 v[12:13], v[12:13], v[24:25]
	v_lshlrev_b32_e32 v24, 16, v80
	v_and_b32_e32 v25, 0xffff0000, v80
	v_pk_add_f32 v[10:11], v[10:11], v[24:25]
	v_lshlrev_b32_e32 v24, 16, v81
	v_and_b32_e32 v25, 0xffff0000, v81
	v_pk_add_f32 v[8:9], v[8:9], v[24:25]
	s_waitcnt vmcnt(6)
	v_lshlrev_b32_e32 v24, 16, v82
	v_and_b32_e32 v25, 0xffff0000, v82
	v_pk_add_f32 v[14:15], v[14:15], v[24:25]
	v_lshlrev_b32_e32 v24, 16, v83
	v_and_b32_e32 v25, 0xffff0000, v83
	v_pk_add_f32 v[12:13], v[12:13], v[24:25]
	v_lshlrev_b32_e32 v24, 16, v84
	v_and_b32_e32 v25, 0xffff0000, v84
	v_pk_add_f32 v[10:11], v[10:11], v[24:25]
	v_lshlrev_b32_e32 v24, 16, v85
	v_and_b32_e32 v25, 0xffff0000, v85
	v_pk_add_f32 v[8:9], v[8:9], v[24:25]
	s_waitcnt vmcnt(5)
	v_lshlrev_b32_e32 v24, 16, v86
	v_and_b32_e32 v25, 0xffff0000, v86
	v_pk_add_f32 v[14:15], v[14:15], v[24:25]
	v_lshlrev_b32_e32 v24, 16, v87
	v_and_b32_e32 v25, 0xffff0000, v87
	v_pk_add_f32 v[12:13], v[12:13], v[24:25]
	v_lshlrev_b32_e32 v24, 16, v88
	v_and_b32_e32 v25, 0xffff0000, v88
	v_pk_add_f32 v[10:11], v[10:11], v[24:25]
	v_lshlrev_b32_e32 v24, 16, v89
	v_and_b32_e32 v25, 0xffff0000, v89
	v_pk_add_f32 v[8:9], v[8:9], v[24:25]
	s_waitcnt vmcnt(4)
	v_lshlrev_b32_e32 v24, 16, v90
	v_and_b32_e32 v25, 0xffff0000, v90
	v_pk_add_f32 v[14:15], v[14:15], v[24:25]
	v_lshlrev_b32_e32 v24, 16, v91
	v_and_b32_e32 v25, 0xffff0000, v91
	v_pk_add_f32 v[12:13], v[12:13], v[24:25]
	v_lshlrev_b32_e32 v24, 16, v92
	v_and_b32_e32 v25, 0xffff0000, v92
	v_pk_add_f32 v[10:11], v[10:11], v[24:25]
	v_lshlrev_b32_e32 v24, 16, v93
	v_and_b32_e32 v25, 0xffff0000, v93
	v_pk_add_f32 v[8:9], v[8:9], v[24:25]
	s_waitcnt vmcnt(3)
	v_lshlrev_b32_e32 v24, 16, v94
	v_and_b32_e32 v25, 0xffff0000, v94
	v_pk_add_f32 v[14:15], v[14:15], v[24:25]
	v_lshlrev_b32_e32 v24, 16, v95
	v_and_b32_e32 v25, 0xffff0000, v95
	v_pk_add_f32 v[12:13], v[12:13], v[24:25]
	v_lshlrev_b32_e32 v24, 16, v96
	v_and_b32_e32 v25, 0xffff0000, v96
	v_pk_add_f32 v[10:11], v[10:11], v[24:25]
	v_lshlrev_b32_e32 v24, 16, v97
	v_and_b32_e32 v25, 0xffff0000, v97
	v_pk_add_f32 v[8:9], v[8:9], v[24:25]
	s_waitcnt vmcnt(2)
	v_lshlrev_b32_e32 v24, 16, v98
	v_and_b32_e32 v25, 0xffff0000, v98
	v_pk_add_f32 v[14:15], v[14:15], v[24:25]
	v_lshlrev_b32_e32 v24, 16, v99
	v_and_b32_e32 v25, 0xffff0000, v99
	v_pk_add_f32 v[12:13], v[12:13], v[24:25]
	v_lshlrev_b32_e32 v24, 16, v100
	v_and_b32_e32 v25, 0xffff0000, v100
	v_pk_add_f32 v[10:11], v[10:11], v[24:25]
	v_lshlrev_b32_e32 v24, 16, v101
	v_and_b32_e32 v25, 0xffff0000, v101
	v_pk_add_f32 v[8:9], v[8:9], v[24:25]
	s_waitcnt vmcnt(1)
	v_lshlrev_b32_e32 v24, 16, v102
	v_and_b32_e32 v25, 0xffff0000, v102
	v_pk_add_f32 v[14:15], v[14:15], v[24:25]
	v_lshlrev_b32_e32 v24, 16, v103
	v_and_b32_e32 v25, 0xffff0000, v103
	v_pk_add_f32 v[12:13], v[12:13], v[24:25]
	v_lshlrev_b32_e32 v24, 16, v104
	v_and_b32_e32 v25, 0xffff0000, v104
	v_pk_add_f32 v[10:11], v[10:11], v[24:25]
	v_lshlrev_b32_e32 v24, 16, v105
	v_and_b32_e32 v25, 0xffff0000, v105
	v_pk_add_f32 v[8:9], v[8:9], v[24:25]
	s_waitcnt vmcnt(0)
	v_lshlrev_b32_e32 v24, 16, v106
	v_and_b32_e32 v25, 0xffff0000, v106
	v_pk_add_f32 v[14:15], v[14:15], v[24:25]
	v_lshlrev_b32_e32 v24, 16, v107
	v_and_b32_e32 v25, 0xffff0000, v107
	v_pk_add_f32 v[12:13], v[12:13], v[24:25]
	v_lshlrev_b32_e32 v24, 16, v108
	v_and_b32_e32 v25, 0xffff0000, v108
	v_pk_add_f32 v[10:11], v[10:11], v[24:25]
	v_lshlrev_b32_e32 v24, 16, v109
	v_and_b32_e32 v25, 0xffff0000, v109
	v_pk_add_f32 v[8:9], v[8:9], v[24:25]
	s_cmp_lg_u32 s8, 0x180000
	s_cbranch_scc1 .LBB0_251
	ds_bpermute_b32 v6, v1, v14
	ds_bpermute_b32 v7, v1, v15
	ds_bpermute_b32 v16, v1, v12
	ds_bpermute_b32 v17, v1, v13
	ds_bpermute_b32 v20, v1, v10
	ds_bpermute_b32 v21, v1, v11
	s_waitcnt lgkmcnt(4)
	v_pk_add_f32 v[6:7], v[14:15], v[6:7]
	ds_bpermute_b32 v14, v22, v6
	s_waitcnt lgkmcnt(3)
	v_pk_add_f32 v[16:17], v[12:13], v[16:17]
	ds_bpermute_b32 v15, v22, v7
	ds_bpermute_b32 v18, v22, v16
	ds_bpermute_b32 v19, v22, v17
	s_waitcnt lgkmcnt(4)
	v_pk_add_f32 v[10:11], v[10:11], v[20:21]
	ds_bpermute_b32 v20, v22, v10
	s_waitcnt lgkmcnt(3)
	v_pk_add_f32 v[6:7], v[6:7], v[14:15]
	ds_bpermute_b32 v21, v22, v11
	s_waitcnt lgkmcnt(2)
	v_pk_add_f32 v[14:15], v[16:17], v[18:19]
	ds_bpermute_b32 v18, v1, v8
	ds_bpermute_b32 v19, v1, v9
	ds_bpermute_b32 v12, v23, v6
	ds_bpermute_b32 v13, v23, v7
	ds_bpermute_b32 v16, v23, v14
	ds_bpermute_b32 v17, v23, v15
	s_waitcnt lgkmcnt(4)
	v_pk_add_f32 v[18:19], v[8:9], v[18:19]
	ds_bpermute_b32 v24, v22, v18
	ds_bpermute_b32 v25, v22, v19
	v_pk_add_f32 v[8:9], v[10:11], v[20:21]
	ds_bpermute_b32 v10, v23, v8
	ds_bpermute_b32 v11, v23, v9
	s_waitcnt lgkmcnt(2)
	v_pk_add_f32 v[18:19], v[18:19], v[24:25]
	ds_bpermute_b32 v20, v23, v18
	ds_bpermute_b32 v21, v23, v19
	s_and_saveexec_b64 s[8:9], s[4:5]
	v_readlane_b32 s14, v253, 49
	v_readlane_b32 s15, v253, 50
	s_cbranch_execz .LBB0_249
	s_ashr_i32 s7, s6, 31
	s_lshl_b64 s[12:13], s[6:7], 8
	v_lshl_add_u64 v[24:25], v[2:3], 0, s[12:13]
	v_pk_add_f32 v[6:7], v[6:7], v[12:13]
	s_mov_b32 s12, 0x3b800000
	v_pk_mul_f32 v[12:13], v[6:7], s[12:13] op_sel_hi:[1,0]
	v_pk_add_f32 v[6:7], v[14:15], v[16:17]
	s_nop 0
	v_pk_mul_f32 v[14:15], v[6:7], s[12:13] op_sel_hi:[1,0]
	s_waitcnt lgkmcnt(2)
	v_pk_add_f32 v[6:7], v[8:9], v[10:11]
	s_waitcnt lgkmcnt(0)
	v_pk_add_f32 v[8:9], v[18:19], v[20:21]
	v_pk_mul_f32 v[6:7], v[6:7], s[12:13] op_sel_hi:[1,0]
	v_pk_mul_f32 v[8:9], v[8:9], s[12:13] op_sel_hi:[1,0]
	global_store_dwordx4 v[24:25], v[12:15], off
	global_store_dwordx4 v[24:25], v[6:9], off offset:16
	s_branch .LBB0_249
